# P4: odd row panels run K as [PB part | SG part] (acc=PB@Wb; mid hook *= sgb/sga; += SG@Wa; epilogue *= sga) so the two halves of the grid hit the gate-load hook at different times
# speedup vs baseline: 1.0073x; 1.0011x over previous
.LBB0_511:
	s_mov_b32 s98, 32
	s_movk_i32 s99, 0x1000
	s_movk_i32 s100, 0x1700
	s_movk_i32 s101, 0x1700
	v_readlane_b32 s0, v254, 2
	s_bitcmp1_b32 s0, 3
	s_cbranch_scc0 .Lp4_norev
	s_mov_b32 s98, 16
	s_mov_b32 s99, 0xfffff000
	s_movk_i32 s100, 0x700
	s_mov_b32 s101, 0xffffff00
	s_mov_b32 s0, s14
	s_mov_b32 s14, s38
	s_mov_b32 s38, s0
	s_mov_b32 s0, s15
	s_mov_b32 s15, s39
	s_mov_b32 s39, s0
.Lp4_norev:
	s_waitcnt vmcnt(34)
	v_lshlrev_b32_e32 v1, 4, v0
	v_and_b32_e32 v2, 32, v0
	v_bitop3_b32 v1, v1, v2, 48 bitop3:0x6c
	v_and_or_b32 v1, v0, 64, v1
	s_waitcnt vmcnt(33)
	v_lshrrev_b32_e32 v4, 1, v1
	v_lshrrev_b32_e32 v1, 1, v0
	s_ashr_i32 s1, s8, 3
	v_and_b32_e32 v2, 24, v1
	v_lshrrev_b32_e32 v1, 5, v0
	v_and_b32_e32 v1, 4, v1
	s_waitcnt vmcnt(30) lgkmcnt(1)
	v_bfe_u32 v5, v0, 2, 2
	s_add_i32 s1, s5, s1
	v_bfe_u32 v3, v0, 2, 4
	v_or3_b32 v5, v1, v5, v2
	v_lshrrev_b32_e32 v1, 3, v0
	s_ashr_i32 s5, s1, 31
	v_and_or_b32 v6, v1, 48, v3
	s_waitcnt vmcnt(28) lgkmcnt(0)
	v_and_or_b32 v7, v1, 32, v5
	s_lshr_b32 s5, s5, 26
	v_mul_u32_u24_e32 v1, 0xc00, v6
	v_mul_u32_u24_e32 v6, 0xc00, v7
	s_add_i32 s5, s1, s5
	v_or_b32_e32 v6, v6, v4
	s_ashr_i32 s9, s5, 6
	s_andn2_b32 s5, s5, 63
	v_lshlrev_b32_e32 v166, 1, v6
	v_bfe_u32 v6, v0, 3, 25
	s_sub_i32 s1, s1, s5
	v_or_b32_e32 v6, 64, v6
	s_movk_i32 s0, 0x70
	s_bfe_i32 s5, s1, 0x80000
	v_and_or_b32 v3, v6, s0, v3
	s_movk_i32 s0, 0x60
	s_bfe_u32 s5, s5, 0x3000c
	v_and_or_b32 v5, v6, s0, v5
	s_lshr_b32 s0, s4, 6
	s_add_i32 s5, s1, s5
	v_mul_u32_u24_e32 v3, 0xc00, v3
	s_lshl_b32 s8, s0, 10
	s_bfe_i32 s10, s5, 0x80000
	v_or_b32_e32 v3, v3, v4
	s_sext_i32_i16 s10, s10
	s_add_i32 s29, s8, 0
	v_lshlrev_b32_e32 v167, 1, v3
	v_mul_u32_u24_e32 v3, 0xc00, v5
	s_and_b32 s5, s5, 0xf8
	s_ashr_i32 s62, s10, 3
	s_mov_b32 s51, 0x20000
	s_add_i32 s35, s29, 0x10000
	v_or_b32_e32 v3, v3, v4
	s_sub_i32 s1, s1, s5
	s_mov_b32 s70, 0xc00000
	s_and_b32 s69, s69, 0xffff
	s_mov_b32 s71, s51
	s_mul_i32 s91, s62, 0x180000
	s_sub_i32 s45, 32, s98
	s_lshl_b32 s45, s45, 8
	s_add_i32 s91, s91, s45
	s_mov_b32 m0, s35
	s_add_i32 s45, s29, 0x12000
	v_lshlrev_b32_e32 v168, 1, v3
	s_lshl_b32 s9, s9, 3
	s_sext_i32_i8 s1, s1
	buffer_load_dwordx4 v166, s[68:71], s91 offen lds
	s_mov_b32 m0, s45
	s_add_i32 s64, s29, 0x14000
	s_add_i32 s63, s9, s1
	buffer_load_dwordx4 v168, s[68:71], s91 offen lds
	s_add_i32 s1, s91, 0xc0000
	s_mov_b32 m0, s64
	s_add_i32 s65, s29, 0x16000
	v_or_b32_e32 v1, v4, v1
	buffer_load_dwordx4 v166, s[68:71], s1 offen lds
	s_mov_b32 m0, s65
	v_lshlrev_b32_e32 v1, 1, v1
	s_mov_b32 s50, 0x3000000
	s_and_b32 s49, s17, 0xffff
	buffer_load_dwordx4 v168, s[68:71], s1 offen lds
	s_mul_i32 s88, s63, 0x180000
	s_sub_i32 s66, 32, s98
	s_lshl_b32 s66, s66, 8
	s_add_i32 s88, s88, s66
	s_mov_b32 m0, s29
	s_add_i32 s66, s29, 0x2000
	buffer_load_dwordx4 v1, s[48:51], s88 offen lds
	s_mov_b32 m0, s66
	s_add_i32 s67, s29, 0x4000
	buffer_load_dwordx4 v167, s[48:51], s88 offen lds
	s_add_i32 s1, s88, 0xc0000
	s_mov_b32 m0, s67
	s_add_i32 s72, s29, 0x6000
	buffer_load_dwordx4 v1, s[48:51], s1 offen lds
	s_mov_b32 m0, s72
	s_mov_b32 s73, 0
	buffer_load_dwordx4 v167, s[48:51], s1 offen lds
	s_lshr_b32 s1, s4, 8
	s_cmp_eq_u32 s1, 1
	s_cselect_b64 s[8:9], -1, 0
	s_cmp_lg_u32 s1, 1
	v_writelane_b32 v254, s78, 23
	s_cbranch_scc1 .LBB0_513
	s_barrier

.LBB0_522:
	v_mov_b32_e32 v4, v2
	v_mov_b32_e32 v5, v2
	s_mul_i32 s86, s85, 0x180000
	s_and_b64 s[4:5], s[0:1], exec
	s_mul_i32 s87, s84, 0x180000
	v_lshl_or_b32 v162, s62, 8, v170
	v_mov_b32_e32 v3, v2
	s_waitcnt vmcnt(38)
	v_mov_b64_e32 v[8:9], v[4:5]
	s_waitcnt vmcnt(34)
	v_mov_b64_e32 v[12:13], v[4:5]
	s_waitcnt vmcnt(22)
	v_mov_b64_e32 v[24:25], v[4:5]
	s_waitcnt vmcnt(18)
	v_mov_b64_e32 v[28:29], v[4:5]
	v_mov_b64_e32 v[40:41], v[4:5]
	v_mov_b64_e32 v[44:45], v[4:5]
	v_mov_b64_e32 v[56:57], v[4:5]
	v_mov_b64_e32 v[60:61], v[4:5]
	v_mov_b64_e32 v[16:17], v[4:5]
	v_mov_b64_e32 v[20:21], v[4:5]
	s_waitcnt vmcnt(16)
	v_mov_b64_e32 v[32:33], v[4:5]
	v_mov_b64_e32 v[36:37], v[4:5]
	v_mov_b64_e32 v[48:49], v[4:5]
	v_mov_b64_e32 v[52:53], v[4:5]
	v_mov_b64_e32 v[64:65], v[4:5]
	v_mov_b64_e32 v[68:69], v[4:5]
	v_mov_b64_e32 v[72:73], v[4:5]
	v_mov_b64_e32 v[76:77], v[4:5]
	v_mov_b64_e32 v[88:89], v[4:5]
	v_mov_b64_e32 v[92:93], v[4:5]
	v_mov_b64_e32 v[104:105], v[4:5]
	v_mov_b64_e32 v[108:109], v[4:5]
	v_mov_b64_e32 v[120:121], v[4:5]
	v_mov_b64_e32 v[124:125], v[4:5]
	v_mov_b64_e32 v[80:81], v[4:5]
	v_mov_b64_e32 v[84:85], v[4:5]
	v_mov_b64_e32 v[96:97], v[4:5]
	v_mov_b64_e32 v[100:101], v[4:5]
	v_mov_b64_e32 v[112:113], v[4:5]
	v_mov_b64_e32 v[116:117], v[4:5]
	v_mov_b64_e32 v[128:129], v[4:5]
	v_mov_b64_e32 v[132:133], v[4:5]
	s_cselect_b32 s89, s86, s88
	s_cselect_b32 s90, s87, s91
	s_sub_i32 s92, 32, s98
	s_lshl_b32 s92, s92, 8
	s_sub_i32 s89, s89, s92
	s_sub_i32 s90, s90, s92
	v_lshl_add_u32 v164, s63, 8, v169
	v_ashrrev_i32_e32 v163, 31, v162
	s_addk_i32 s91, 0x100
	s_mov_b32 s92, 0
	s_mov_b64 s[62:63], 0
	v_mov_b64_e32 v[6:7], v[2:3]
	v_mov_b64_e32 v[10:11], v[2:3]
	v_mov_b64_e32 v[22:23], v[2:3]
	v_mov_b64_e32 v[26:27], v[2:3]
	v_mov_b64_e32 v[38:39], v[2:3]
	v_mov_b64_e32 v[42:43], v[2:3]
	v_mov_b64_e32 v[54:55], v[2:3]
	v_mov_b64_e32 v[58:59], v[2:3]
	v_mov_b64_e32 v[14:15], v[2:3]
	v_mov_b64_e32 v[18:19], v[2:3]
	v_mov_b64_e32 v[30:31], v[2:3]
	v_mov_b64_e32 v[34:35], v[2:3]
	v_mov_b64_e32 v[46:47], v[2:3]
	v_mov_b64_e32 v[50:51], v[2:3]
	v_mov_b64_e32 v[62:63], v[2:3]
	v_mov_b64_e32 v[66:67], v[2:3]
	v_mov_b64_e32 v[70:71], v[2:3]
	v_mov_b64_e32 v[74:75], v[2:3]
	v_mov_b64_e32 v[86:87], v[2:3]
	v_mov_b64_e32 v[90:91], v[2:3]
	v_mov_b64_e32 v[102:103], v[2:3]
	v_mov_b64_e32 v[106:107], v[2:3]
	v_mov_b64_e32 v[118:119], v[2:3]
	v_mov_b64_e32 v[122:123], v[2:3]
	v_mov_b64_e32 v[78:79], v[2:3]
	v_mov_b64_e32 v[82:83], v[2:3]
	v_mov_b64_e32 v[94:95], v[2:3]
	v_mov_b64_e32 v[98:99], v[2:3]
	v_mov_b64_e32 v[110:111], v[2:3]
	v_mov_b64_e32 v[114:115], v[2:3]
	v_mov_b64_e32 v[126:127], v[2:3]
	v_mov_b64_e32 v[130:131], v[2:3]
	s_branch .LBB0_524
.LBB0_523:
	s_mov_b32 s92, s98
	s_and_b64 vcc, exec, s[4:5]
	s_mov_b64 s[62:63], -1
	s_cbranch_vccz .LBB0_529

.LBB0_526:
	s_and_b64 s[62:63], s[62:63], exec
	s_cselect_b32 s62, 48, s98
	s_cmp_eq_u32 s92, s62
	s_cbranch_scc1 .LBB0_523
	s_cmp_eq_u32 s92, 0
	s_cselect_b32 s63, 0, s99
	s_cselect_b32 s93, s100, s101
	s_mov_b32 s94, s88
	s_mov_b32 s95, s91

	.amdhsa_kernel _Z14fwd_megakernel6Params
		.amdhsa_group_segment_fixed_size 0
		.amdhsa_private_segment_fixed_size 0
		.amdhsa_kernarg_size 456
		.amdhsa_user_sgpr_count 2
		.amdhsa_user_sgpr_dispatch_ptr 0
		.amdhsa_user_sgpr_queue_ptr 0
		.amdhsa_user_sgpr_kernarg_segment_ptr 1
		.amdhsa_user_sgpr_dispatch_id 0
		.amdhsa_user_sgpr_kernarg_preload_length 0
		.amdhsa_user_sgpr_kernarg_preload_offset 0
		.amdhsa_user_sgpr_private_segment_size 0
		.amdhsa_uses_dynamic_stack 0
		.amdhsa_enable_private_segment 0
		.amdhsa_system_sgpr_workgroup_id_x 1
		.amdhsa_system_sgpr_workgroup_id_y 0
		.amdhsa_system_sgpr_workgroup_id_z 0
		.amdhsa_system_sgpr_workgroup_info 0
		.amdhsa_system_vgpr_workitem_id 0
		.amdhsa_next_free_vgpr 255
		.amdhsa_next_free_sgpr 102
		.amdhsa_accum_offset 256
		.amdhsa_reserve_vcc 1
		.amdhsa_float_round_mode_32 0
		.amdhsa_float_round_mode_16_64 0
		.amdhsa_float_denorm_mode_32 3
		.amdhsa_float_denorm_mode_16_64 3
		.amdhsa_dx10_clamp 1
		.amdhsa_ieee_mode 1
		.amdhsa_fp16_overflow 0
		.amdhsa_tg_split 0
		.amdhsa_exception_fp_ieee_invalid_op 0
		.amdhsa_exception_fp_denorm_src 0
		.amdhsa_exception_fp_ieee_div_zero 0
		.amdhsa_exception_fp_ieee_overflow 0
		.amdhsa_exception_fp_ieee_underflow 0
		.amdhsa_exception_fp_ieee_inexact 0
		.amdhsa_exception_int_div_zero 0
	.end_amdhsa_kernel

amdhsa.kernels:
  - .agpr_count:     0
    .args:
      - .offset:         0
        .size:           200
        .value_kind:     by_value
      - .offset:         200
        .size:           4
        .value_kind:     hidden_block_count_x
      - .offset:         204
        .size:           4
        .value_kind:     hidden_block_count_y
      - .offset:         208
        .size:           4
        .value_kind:     hidden_block_count_z
      - .offset:         212
        .size:           2
        .value_kind:     hidden_group_size_x
      - .offset:         214
        .size:           2
        .value_kind:     hidden_group_size_y
      - .offset:         216
        .size:           2
        .value_kind:     hidden_group_size_z
      - .offset:         218
        .size:           2
        .value_kind:     hidden_remainder_x
      - .offset:         220
        .size:           2
        .value_kind:     hidden_remainder_y
      - .offset:         222
        .size:           2
        .value_kind:     hidden_remainder_z
      - .offset:         240
        .size:           8
        .value_kind:     hidden_global_offset_x
      - .offset:         248
        .size:           8
        .value_kind:     hidden_global_offset_y
      - .offset:         256
        .size:           8
        .value_kind:     hidden_global_offset_z
      - .offset:         264
        .size:           2
        .value_kind:     hidden_grid_dims
      - .offset:         320
        .size:           4
        .value_kind:     hidden_dynamic_lds_size
    .group_segment_fixed_size: 0
    .kernarg_segment_align: 8
    .kernarg_segment_size: 456
    .language:       OpenCL C
    .language_version:
      - 2
      - 0
    .max_flat_workgroup_size: 512
    .name:           _Z14fwd_megakernel6Params
    .private_segment_fixed_size: 0
    .sgpr_count:     108
    .sgpr_spill_count: 32
    .symbol:         _Z14fwd_megakernel6Params.kd
    .uniform_work_group_size: 1
    .uses_dynamic_stack: false
    .vgpr_count:     255
    .vgpr_spill_count: 0
    .wavefront_size: 64
